# static s_setprio 1 for workgroups with bit 8 of the workgroup id clear (first half of the grid)
# speedup vs baseline: 1.0050x; 1.0050x over previous
; #define LAS __attribute__((address_space(3)))
; __global__ void __launch_bounds__(256, 2) mega_kernel(Params P, int ph_lo, int ph_hi) {
;   __shared__ __attribute__((aligned(16))) char smem[73728];
;   __shared__ uint4 xb_words;
;   if (threadIdx.x == 0) xb_words = make_uint4(0u, 0u, 0u, 0u);
;   __syncthreads();
;   XcdBarrier xb = xcd_barrier_post(P.bar, (volatile LAS unsigned*)&xb_words);
_Z11mega_kernel6Paramsii:
	s_bitcmp0_b32 s2, 8
	s_cbranch_scc0 .Lprio_skip
	s_setprio 1
.Lprio_skip:
	s_load_dwordx2 s[4:5], s[0:1], 0x1c8
	v_and_b32_e32 v202, 0x3ff, v0
	s_waitcnt lgkmcnt(0)
	v_writelane_b32 v251, s4, 0
	s_nop 1
	v_writelane_b32 v251, s5, 1
	s_load_dwordx4 s[4:7], s[0:1], 0x1b8
	s_waitcnt lgkmcnt(0)
	v_writelane_b32 v251, s4, 2
	s_nop 1
	v_writelane_b32 v251, s5, 3
	v_writelane_b32 v251, s6, 4
	v_writelane_b32 v251, s7, 5
	v_cmp_eq_u32_e64 s[4:5], 0, v202
	s_mov_b64 s[6:7], exec
	s_nop 0
	v_writelane_b32 v251, s4, 6
	s_nop 1
	v_writelane_b32 v251, s5, 7
	s_and_b64 s[4:5], s[6:7], s[4:5]
	s_mov_b64 exec, s[4:5]
	s_cbranch_execz .LBB0_2
	v_mov_b32_e32 v2, 0
	v_mov_b32_e32 v3, v2
	v_mov_b32_e32 v4, v2
	v_mov_b32_e32 v5, v2
	v_mov_b32_e32 v1, 0x12000
	ds_write_b128 v1, v[2:5]
